# grid barrier: s_sleep removed from the poll loops (re-poll as soon as the previous poll returns)
# speedup vs baseline: 1.0014x; 1.0014x over previous
; __global__ void __launch_bounds__(512, 2) fwd_megakernel(Params p) {
;     ...
;     if (p.ws == nullptr) grid.sync();
.LBB0_50:
	s_nop 0
	global_load_dword v2, v0, s[4:5] offset:32 sc1
	s_waitcnt vmcnt(0)
	v_and_b32_e32 v2, 0xffff0000, v2
	v_cmp_ne_u32_e32 vcc, v2, v1
	s_or_b64 s[6:7], vcc, s[6:7]
	s_andn2_b64 exec, exec, s[6:7]
	s_cbranch_execnz .LBB0_50

; __device__ __forceinline__ unsigned xb_ld(unsigned* p)              { return __hip_atomic_load(p, __ATOMIC_RELAXED, __HIP_MEMORY_SCOPE_AGENT); }
; __device__ __forceinline__ void xcd_barrier_complete(unsigned* bar, unsigned x, unsigned& nloc, unsigned& nx) {
;     const unsigned G = gridDim.x * gridDim.y * gridDim.z;
;     unsigned sum, cnt, mine, sp = 0u;
;     for (;;) {
;         sum = 0u; cnt = 0u; mine = 0u;
; #pragma unroll
;         for (unsigned j = 0; j < 16; ++j) { const unsigned c = xb_ld(&bar[XB_XCNT(j)]); sum += c; cnt += (c > 0u) ? 1u : 0u; mine = (j == x) ? c : mine; }
;         if (sum == G) break;
;         __builtin_amdgcn_s_sleep(1);
;         if ((++sp & 255u) == 0u) { if (xb_ld(&bar[XB_TMO])) break; if (sp > XB_SPIN_CAP) { atomicAdd(&bar[XB_TMO], 1u); break; } }
;     }
;     nloc = mine > 0u ? mine : 1u; nx = cnt > 0u ? cnt : 1u;
; }
.LBB0_58:
	v_readlane_b32 s2, v251, 60
	v_readlane_b32 s3, v251, 61
	v_readlane_b32 s4, v251, 57
	s_waitcnt lgkmcnt(0)
	s_nop 2
	global_load_dword v0, v16, s[2:3] sc1
	v_readlane_b32 s2, v251, 62
	v_readlane_b32 s3, v251, 63
	s_nop 4
	global_load_dword v1, v16, s[2:3] sc1
	v_readlane_b32 s2, v252, 0
	v_readlane_b32 s3, v252, 1
	s_nop 4
	global_load_dword v2, v16, s[2:3] sc1
	v_readlane_b32 s2, v252, 2
	v_readlane_b32 s3, v252, 3
	s_nop 4
	global_load_dword v3, v16, s[2:3] sc1
	v_readlane_b32 s2, v252, 4
	v_readlane_b32 s3, v252, 5
	s_nop 4
	global_load_dword v4, v16, s[2:3] sc1
	v_readlane_b32 s2, v252, 6
	v_readlane_b32 s3, v252, 7
	s_nop 4
	global_load_dword v5, v16, s[2:3] sc1
	v_readlane_b32 s2, v252, 8
	v_readlane_b32 s3, v252, 9
	s_nop 4
	global_load_dword v6, v16, s[2:3] sc1
	v_readlane_b32 s2, v252, 10
	v_readlane_b32 s3, v252, 11
	s_nop 4
	global_load_dword v7, v16, s[2:3] sc1
	v_readlane_b32 s2, v252, 12
	v_readlane_b32 s3, v252, 13
	s_nop 4
	global_load_dword v8, v16, s[2:3] sc1
	v_readlane_b32 s2, v252, 14
	v_readlane_b32 s3, v252, 15
	s_nop 4
	global_load_dword v9, v16, s[2:3] sc1
	v_readlane_b32 s2, v252, 16
	v_readlane_b32 s3, v252, 17
	s_nop 4
	global_load_dword v10, v16, s[2:3] sc1
	v_readlane_b32 s2, v252, 18
	v_readlane_b32 s3, v252, 19
	s_nop 4
	global_load_dword v11, v16, s[2:3] sc1
	v_readlane_b32 s2, v252, 20
	v_readlane_b32 s3, v252, 21
	s_nop 4
	global_load_dword v12, v16, s[2:3] sc1
	v_readlane_b32 s2, v252, 22
	v_readlane_b32 s3, v252, 23
	s_nop 4
	global_load_dword v13, v16, s[2:3] sc1
	v_readlane_b32 s2, v252, 24
	v_readlane_b32 s3, v252, 25
	s_nop 4
	global_load_dword v14, v16, s[2:3] sc1
	v_readlane_b32 s2, v252, 26
	v_readlane_b32 s3, v252, 27
	s_nop 4
	global_load_dword v15, v16, s[2:3] sc1
	s_mov_b64 s[2:3], -1
	s_waitcnt vmcnt(0)
	v_add_u32_e32 v17, v1, v0
	v_add_u32_e32 v17, v17, v2
	v_add_u32_e32 v17, v17, v3
	v_add_u32_e32 v17, v17, v4
	v_add_u32_e32 v17, v17, v5
	v_add_u32_e32 v17, v17, v6
	v_add_u32_e32 v17, v17, v7
	v_add_u32_e32 v17, v17, v8
	v_add_u32_e32 v17, v17, v9
	v_add_u32_e32 v17, v17, v10
	v_add_u32_e32 v17, v17, v11
	v_add_u32_e32 v17, v17, v12
	v_add_u32_e32 v17, v17, v13
	v_add_u32_e32 v17, v17, v14
	v_add_u32_e32 v17, v17, v15
	v_cmp_eq_u32_e32 vcc, s4, v17
	s_mov_b64 s[4:5], -1
	s_cbranch_vccnz .LBB0_57
	s_and_b32 s2, s8, 0xff
	s_cmp_eq_u32 s2, 0
	s_mov_b64 s[2:3], -1
	s_mov_b64 s[6:7], -1
	s_nop 0
	s_cbranch_scc0 .LBB0_62
	v_readlane_b32 s2, v251, 58
	v_readlane_b32 s3, v251, 59
	s_nop 4
	global_load_dword v17, v16, s[2:3] sc1
	s_waitcnt vmcnt(0)
	v_cmp_eq_u32_e32 vcc, 0, v17
	s_cbranch_vccnz .LBB0_64
	s_mov_b64 s[6:7], 0
	s_mov_b64 s[2:3], -1

; __device__ __forceinline__ unsigned xb_ld(unsigned* p)              { return __hip_atomic_load(p, __ATOMIC_RELAXED, __HIP_MEMORY_SCOPE_AGENT); }
; __device__ __forceinline__ unsigned xb_add(unsigned* p, unsigned v) { return __hip_atomic_fetch_add(p, v, __ATOMIC_RELAXED, __HIP_MEMORY_SCOPE_AGENT); }
; #define XB_SPIN(cond, bar) do { unsigned _sp = 0; while (cond) { __builtin_amdgcn_s_sleep(1); \
;     if ((++_sp & 255u) == 0u) { if (xb_ld(&(bar)[XB_TMO])) break; if (_sp > XB_SPIN_CAP) { atomicAdd(&(bar)[XB_TMO], 1u); break; } } } } while (0)
; __device__ __forceinline__ void xcd_barrier(const XcdBarrier& b) {
;     ...
;             const unsigned tg = og / nx;
;             if (og + 1u == (tg + 1u) * nx) xb_add(&bar[XB_TOPGEN], 1u);
;             else XB_SPIN(xb_ld(&bar[XB_TOPGEN]) == tg, bar);
;             __builtin_amdgcn_fence(__ATOMIC_ACQUIRE, "agent");
;             xb_add(&bar[XB_XGEN(b.x)], 1u);
;             asm volatile("s_waitcnt vmcnt(0)" ::: "memory");
;         } else {
;             XB_SPIN(xb_ld(&bar[XB_XGEN(b.x)]) == gen, bar);
;             __builtin_amdgcn_fence(__ATOMIC_ACQUIRE, "agent");
.LBB0_76:
	s_and_b32 s12, s15, 0xff
	s_mov_b64 s[10:11], -1
	s_cmp_lg_u32 s12, 0
	s_mov_b64 s[16:17], -1
	s_nop 0
	s_cbranch_scc1 .LBB0_79
	v_readlane_b32 s12, v251, 58
	v_readlane_b32 s13, v251, 59
	s_nop 4
	global_load_dword v2, v0, s[12:13] sc1
	s_waitcnt vmcnt(0)
	v_cmp_eq_u32_e32 vcc, 0, v2
	s_cbranch_vccnz .LBB0_81
	s_mov_b64 s[16:17], 0
	s_mov_b64 s[12:13], -1

; __device__ __forceinline__ unsigned xb_ld(unsigned* p)              { return __hip_atomic_load(p, __ATOMIC_RELAXED, __HIP_MEMORY_SCOPE_AGENT); }
; __device__ __forceinline__ unsigned xb_add(unsigned* p, unsigned v) { return __hip_atomic_fetch_add(p, v, __ATOMIC_RELAXED, __HIP_MEMORY_SCOPE_AGENT); }
; #define XB_SPIN(cond, bar) do { unsigned _sp = 0; while (cond) { __builtin_amdgcn_s_sleep(1); \
;     if ((++_sp & 255u) == 0u) { if (xb_ld(&(bar)[XB_TMO])) break; if (_sp > XB_SPIN_CAP) { atomicAdd(&(bar)[XB_TMO], 1u); break; } } } } while (0)
; __device__ __forceinline__ void xcd_barrier(const XcdBarrier& b) {
;     ...
;             const unsigned tg = og / nx;
;             if (og + 1u == (tg + 1u) * nx) xb_add(&bar[XB_TOPGEN], 1u);
;             else XB_SPIN(xb_ld(&bar[XB_TOPGEN]) == tg, bar);
;             __builtin_amdgcn_fence(__ATOMIC_ACQUIRE, "agent");
;             xb_add(&bar[XB_XGEN(b.x)], 1u);
;             asm volatile("s_waitcnt vmcnt(0)" ::: "memory");
;         } else {
;             XB_SPIN(xb_ld(&bar[XB_XGEN(b.x)]) == gen, bar);
;             __builtin_amdgcn_fence(__ATOMIC_ACQUIRE, "agent");
.LBB0_93:
	s_and_b32 s10, s15, 0xff
	s_cmp_lg_u32 s10, 0
	s_mov_b64 s[12:13], -1
	s_nop 0
	s_cbranch_scc1 .LBB0_96
	v_readlane_b32 s10, v251, 58
	v_readlane_b32 s11, v251, 59
	s_nop 4
	global_load_dword v1, v0, s[10:11] sc1
	s_waitcnt vmcnt(0)
	v_cmp_eq_u32_e32 vcc, 0, v1
	s_cbranch_vccnz .LBB0_98
	s_mov_b64 s[12:13], 0
	s_mov_b64 s[10:11], -1

; __device__ __forceinline__ unsigned xb_ld(unsigned* p)              { return __hip_atomic_load(p, __ATOMIC_RELAXED, __HIP_MEMORY_SCOPE_AGENT); }
; __device__ __forceinline__ void xcd_barrier_complete(unsigned* bar, unsigned x, unsigned& nloc, unsigned& nx) {
;     const unsigned G = gridDim.x * gridDim.y * gridDim.z;
;     unsigned sum, cnt, mine, sp = 0u;
;     for (;;) {
;         sum = 0u; cnt = 0u; mine = 0u;
; #pragma unroll
;         for (unsigned j = 0; j < 16; ++j) { const unsigned c = xb_ld(&bar[XB_XCNT(j)]); sum += c; cnt += (c > 0u) ? 1u : 0u; mine = (j == x) ? c : mine; }
;         if (sum == G) break;
;         __builtin_amdgcn_s_sleep(1);
;         if ((++sp & 255u) == 0u) { if (xb_ld(&bar[XB_TMO])) break; if (sp > XB_SPIN_CAP) { atomicAdd(&bar[XB_TMO], 1u); break; } }
;     }
;     nloc = mine > 0u ? mine : 1u; nx = cnt > 0u ? cnt : 1u;
; }
.LBB0_228:
	v_readlane_b32 s12, v251, 60
	v_readlane_b32 s13, v251, 61
	v_readlane_b32 s5, v251, 57
	s_mov_b64 s[24:25], -1
	s_waitcnt lgkmcnt(0)
	s_nop 1
	global_load_dword v0, v185, s[12:13] sc1
	v_readlane_b32 s12, v251, 62
	v_readlane_b32 s13, v251, 63
	s_nop 4
	global_load_dword v1, v185, s[12:13] sc1
	v_readlane_b32 s12, v252, 0
	v_readlane_b32 s13, v252, 1
	s_waitcnt vmcnt(0)
	v_add_u32_e32 v16, v1, v0
	s_nop 2
	global_load_dword v2, v185, s[12:13] sc1
	v_readlane_b32 s12, v252, 2
	v_readlane_b32 s13, v252, 3
	s_waitcnt vmcnt(0)
	v_add_u32_e32 v16, v16, v2
	s_nop 2
	global_load_dword v3, v185, s[12:13] sc1
	v_readlane_b32 s12, v252, 4
	v_readlane_b32 s13, v252, 5
	s_waitcnt vmcnt(0)
	v_add_u32_e32 v16, v16, v3
	s_nop 2
	global_load_dword v4, v185, s[12:13] sc1
	v_readlane_b32 s12, v252, 6
	v_readlane_b32 s13, v252, 7
	s_waitcnt vmcnt(0)
	v_add_u32_e32 v16, v16, v4
	s_nop 2
	global_load_dword v5, v185, s[12:13] sc1
	v_readlane_b32 s12, v252, 8
	v_readlane_b32 s13, v252, 9
	s_waitcnt vmcnt(0)
	v_add_u32_e32 v16, v16, v5
	s_nop 2
	global_load_dword v6, v185, s[12:13] sc1
	v_readlane_b32 s12, v252, 10
	v_readlane_b32 s13, v252, 11
	s_waitcnt vmcnt(0)
	v_add_u32_e32 v16, v16, v6
	s_nop 2
	global_load_dword v7, v185, s[12:13] sc1
	v_readlane_b32 s12, v252, 12
	v_readlane_b32 s13, v252, 13
	s_waitcnt vmcnt(0)
	v_add_u32_e32 v16, v16, v7
	s_nop 2
	global_load_dword v8, v185, s[12:13] sc1
	v_readlane_b32 s12, v252, 14
	v_readlane_b32 s13, v252, 15
	s_waitcnt vmcnt(0)
	v_add_u32_e32 v16, v16, v8
	s_nop 2
	global_load_dword v9, v185, s[12:13] sc1
	v_readlane_b32 s12, v252, 16
	v_readlane_b32 s13, v252, 17
	s_waitcnt vmcnt(0)
	v_add_u32_e32 v16, v16, v9
	s_nop 2
	global_load_dword v10, v185, s[12:13] sc1
	v_readlane_b32 s12, v252, 18
	v_readlane_b32 s13, v252, 19
	s_waitcnt vmcnt(0)
	v_add_u32_e32 v16, v16, v10
	s_nop 2
	global_load_dword v11, v185, s[12:13] sc1
	v_readlane_b32 s12, v252, 20
	v_readlane_b32 s13, v252, 21
	s_waitcnt vmcnt(0)
	v_add_u32_e32 v16, v16, v11
	s_nop 2
	global_load_dword v12, v185, s[12:13] sc1
	v_readlane_b32 s12, v252, 22
	v_readlane_b32 s13, v252, 23
	s_waitcnt vmcnt(0)
	v_add_u32_e32 v16, v16, v12
	s_nop 2
	global_load_dword v13, v185, s[12:13] sc1
	v_readlane_b32 s12, v252, 24
	v_readlane_b32 s13, v252, 25
	s_waitcnt vmcnt(0)
	v_add_u32_e32 v16, v16, v13
	s_nop 2
	global_load_dword v14, v185, s[12:13] sc1
	v_readlane_b32 s12, v252, 26
	v_readlane_b32 s13, v252, 27
	s_waitcnt vmcnt(0)
	v_add_u32_e32 v16, v16, v14
	s_nop 2
	global_load_dword v15, v185, s[12:13] sc1
	s_mov_b64 s[12:13], -1
	s_waitcnt vmcnt(0)
	v_add_u32_e32 v16, v16, v15
	v_cmp_eq_u32_e32 vcc, s5, v16
	s_cbranch_vccnz .LBB0_227
	s_and_b32 s5, s0, 0xff
	s_cmp_eq_u32 s5, 0
	s_mov_b64 s[26:27], -1
	s_nop 0
	s_cbranch_scc0 .LBB0_232
	v_readlane_b32 s12, v251, 58
	v_readlane_b32 s13, v251, 59
	s_nop 4
	global_load_dword v16, v185, s[12:13] sc1
	s_waitcnt vmcnt(0)
	v_cmp_eq_u32_e32 vcc, 0, v16
	s_cbranch_vccnz .LBB0_234
	s_mov_b64 s[26:27], 0
	s_mov_b64 s[12:13], -1

; __device__ __forceinline__ unsigned xb_ld(unsigned* p)              { return __hip_atomic_load(p, __ATOMIC_RELAXED, __HIP_MEMORY_SCOPE_AGENT); }
; __device__ __forceinline__ unsigned xb_add(unsigned* p, unsigned v) { return __hip_atomic_fetch_add(p, v, __ATOMIC_RELAXED, __HIP_MEMORY_SCOPE_AGENT); }
; #define XB_SPIN(cond, bar) do { unsigned _sp = 0; while (cond) { __builtin_amdgcn_s_sleep(1); \
;     if ((++_sp & 255u) == 0u) { if (xb_ld(&(bar)[XB_TMO])) break; if (_sp > XB_SPIN_CAP) { atomicAdd(&(bar)[XB_TMO], 1u); break; } } } } while (0)
; __device__ __forceinline__ void xcd_barrier(const XcdBarrier& b) {
;     ...
;             const unsigned tg = og / nx;
;             if (og + 1u == (tg + 1u) * nx) xb_add(&bar[XB_TOPGEN], 1u);
;             else XB_SPIN(xb_ld(&bar[XB_TOPGEN]) == tg, bar);
;             __builtin_amdgcn_fence(__ATOMIC_ACQUIRE, "agent");
;             xb_add(&bar[XB_XGEN(b.x)], 1u);
;             asm volatile("s_waitcnt vmcnt(0)" ::: "memory");
;         } else {
;             XB_SPIN(xb_ld(&bar[XB_XGEN(b.x)]) == gen, bar);
;             __builtin_amdgcn_fence(__ATOMIC_ACQUIRE, "agent");
.LBB0_246:
	s_and_b32 s5, s0, 0xff
	s_mov_b64 s[36:37], -1
	s_cmp_lg_u32 s5, 0
	s_mov_b64 s[40:41], -1
	s_nop 0
	s_cbranch_scc1 .LBB0_249
	v_readlane_b32 s38, v251, 58
	v_readlane_b32 s39, v251, 59
	s_nop 4
	global_load_dword v0, v185, s[38:39] sc1
	s_waitcnt vmcnt(0)
	v_cmp_eq_u32_e32 vcc, 0, v0
	s_cbranch_vccnz .LBB0_251
	s_mov_b64 s[40:41], 0
	s_mov_b64 s[38:39], -1

; __device__ __forceinline__ unsigned xb_ld(unsigned* p)              { return __hip_atomic_load(p, __ATOMIC_RELAXED, __HIP_MEMORY_SCOPE_AGENT); }
; __device__ __forceinline__ void xcd_barrier_complete(unsigned* bar, unsigned x, unsigned& nloc, unsigned& nx) {
;     const unsigned G = gridDim.x * gridDim.y * gridDim.z;
;     unsigned sum, cnt, mine, sp = 0u;
;     for (;;) {
;         sum = 0u; cnt = 0u; mine = 0u;
; #pragma unroll
;         for (unsigned j = 0; j < 16; ++j) { const unsigned c = xb_ld(&bar[XB_XCNT(j)]); sum += c; cnt += (c > 0u) ? 1u : 0u; mine = (j == x) ? c : mine; }
;         if (sum == G) break;
;         __builtin_amdgcn_s_sleep(1);
;         if ((++sp & 255u) == 0u) { if (xb_ld(&bar[XB_TMO])) break; if (sp > XB_SPIN_CAP) { atomicAdd(&bar[XB_TMO], 1u); break; } }
;     }
;     nloc = mine > 0u ? mine : 1u; nx = cnt > 0u ? cnt : 1u;
; }
.LBB0_1265:
	v_readlane_b32 s12, v251, 60
	v_readlane_b32 s13, v251, 61
	v_readlane_b32 s7, v251, 57
	s_mov_b64 s[24:25], -1
	s_waitcnt lgkmcnt(0)
	s_nop 1
	global_load_dword v0, v185, s[12:13] sc1
	v_readlane_b32 s12, v251, 62
	v_readlane_b32 s13, v251, 63
	s_nop 4
	global_load_dword v1, v185, s[12:13] sc1
	v_readlane_b32 s12, v252, 0
	v_readlane_b32 s13, v252, 1
	s_waitcnt vmcnt(0)
	v_add_u32_e32 v16, v1, v0
	s_nop 2
	global_load_dword v2, v185, s[12:13] sc1
	v_readlane_b32 s12, v252, 2
	v_readlane_b32 s13, v252, 3
	s_waitcnt vmcnt(0)
	v_add_u32_e32 v16, v16, v2
	s_nop 2
	global_load_dword v3, v185, s[12:13] sc1
	v_readlane_b32 s12, v252, 4
	v_readlane_b32 s13, v252, 5
	s_waitcnt vmcnt(0)
	v_add_u32_e32 v16, v16, v3
	s_nop 2
	global_load_dword v4, v185, s[12:13] sc1
	v_readlane_b32 s12, v252, 6
	v_readlane_b32 s13, v252, 7
	s_waitcnt vmcnt(0)
	v_add_u32_e32 v16, v16, v4
	s_nop 2
	global_load_dword v5, v185, s[12:13] sc1
	v_readlane_b32 s12, v252, 8
	v_readlane_b32 s13, v252, 9
	s_waitcnt vmcnt(0)
	v_add_u32_e32 v16, v16, v5
	s_nop 2
	global_load_dword v6, v185, s[12:13] sc1
	v_readlane_b32 s12, v252, 10
	v_readlane_b32 s13, v252, 11
	s_waitcnt vmcnt(0)
	v_add_u32_e32 v16, v16, v6
	s_nop 2
	global_load_dword v7, v185, s[12:13] sc1
	v_readlane_b32 s12, v252, 12
	v_readlane_b32 s13, v252, 13
	s_waitcnt vmcnt(0)
	v_add_u32_e32 v16, v16, v7
	s_nop 2
	global_load_dword v8, v185, s[12:13] sc1
	v_readlane_b32 s12, v252, 14
	v_readlane_b32 s13, v252, 15
	s_waitcnt vmcnt(0)
	v_add_u32_e32 v16, v16, v8
	s_nop 2
	global_load_dword v9, v185, s[12:13] sc1
	v_readlane_b32 s12, v252, 16
	v_readlane_b32 s13, v252, 17
	s_waitcnt vmcnt(0)
	v_add_u32_e32 v16, v16, v9
	s_nop 2
	global_load_dword v10, v185, s[12:13] sc1
	v_readlane_b32 s12, v252, 18
	v_readlane_b32 s13, v252, 19
	s_waitcnt vmcnt(0)
	v_add_u32_e32 v16, v16, v10
	s_nop 2
	global_load_dword v11, v185, s[12:13] sc1
	v_readlane_b32 s12, v252, 20
	v_readlane_b32 s13, v252, 21
	s_waitcnt vmcnt(0)
	v_add_u32_e32 v16, v16, v11
	s_nop 2
	global_load_dword v12, v185, s[12:13] sc1
	v_readlane_b32 s12, v252, 22
	v_readlane_b32 s13, v252, 23
	s_waitcnt vmcnt(0)
	v_add_u32_e32 v16, v16, v12
	s_nop 2
	global_load_dword v13, v185, s[12:13] sc1
	v_readlane_b32 s12, v252, 24
	v_readlane_b32 s13, v252, 25
	s_waitcnt vmcnt(0)
	v_add_u32_e32 v16, v16, v13
	s_nop 2
	global_load_dword v14, v185, s[12:13] sc1
	v_readlane_b32 s12, v252, 26
	v_readlane_b32 s13, v252, 27
	s_waitcnt vmcnt(0)
	v_add_u32_e32 v16, v16, v14
	s_nop 2
	global_load_dword v15, v185, s[12:13] sc1
	s_mov_b64 s[12:13], -1
	s_waitcnt vmcnt(0)
	v_add_u32_e32 v16, v16, v15
	v_cmp_eq_u32_e32 vcc, s7, v16
	s_cbranch_vccnz .LBB0_1264
	s_and_b32 s7, s0, 0xff
	s_cmp_eq_u32 s7, 0
	s_mov_b64 s[26:27], -1
	s_nop 0
	s_cbranch_scc0 .LBB0_1269
	v_readlane_b32 s12, v251, 58
	v_readlane_b32 s13, v251, 59
	s_nop 4
	global_load_dword v16, v185, s[12:13] sc1
	s_waitcnt vmcnt(0)
	v_cmp_eq_u32_e32 vcc, 0, v16
	s_cbranch_vccnz .LBB0_1271
	s_mov_b64 s[26:27], 0
	s_mov_b64 s[12:13], -1

; __device__ __forceinline__ unsigned xb_ld(unsigned* p)              { return __hip_atomic_load(p, __ATOMIC_RELAXED, __HIP_MEMORY_SCOPE_AGENT); }
; __device__ __forceinline__ unsigned xb_add(unsigned* p, unsigned v) { return __hip_atomic_fetch_add(p, v, __ATOMIC_RELAXED, __HIP_MEMORY_SCOPE_AGENT); }
; #define XB_SPIN(cond, bar) do { unsigned _sp = 0; while (cond) { __builtin_amdgcn_s_sleep(1); \
;     if ((++_sp & 255u) == 0u) { if (xb_ld(&(bar)[XB_TMO])) break; if (_sp > XB_SPIN_CAP) { atomicAdd(&(bar)[XB_TMO], 1u); break; } } } } while (0)
; __device__ __forceinline__ void xcd_barrier(const XcdBarrier& b) {
;     ...
;             const unsigned tg = og / nx;
;             if (og + 1u == (tg + 1u) * nx) xb_add(&bar[XB_TOPGEN], 1u);
;             else XB_SPIN(xb_ld(&bar[XB_TOPGEN]) == tg, bar);
;             __builtin_amdgcn_fence(__ATOMIC_ACQUIRE, "agent");
;             xb_add(&bar[XB_XGEN(b.x)], 1u);
;             asm volatile("s_waitcnt vmcnt(0)" ::: "memory");
;         } else {
;             XB_SPIN(xb_ld(&bar[XB_XGEN(b.x)]) == gen, bar);
;             __builtin_amdgcn_fence(__ATOMIC_ACQUIRE, "agent");
.LBB0_1283:
	s_and_b32 s7, s0, 0xff
	s_mov_b64 s[36:37], -1
	s_cmp_lg_u32 s7, 0
	s_mov_b64 s[40:41], -1
	s_nop 0
	s_cbranch_scc1 .LBB0_1286
	v_readlane_b32 s38, v251, 58
	v_readlane_b32 s39, v251, 59
	s_nop 4
	global_load_dword v0, v185, s[38:39] sc1
	s_waitcnt vmcnt(0)
	v_cmp_eq_u32_e32 vcc, 0, v0
	s_cbranch_vccnz .LBB0_1288
	s_mov_b64 s[40:41], 0
	s_mov_b64 s[38:39], -1

; __device__ __forceinline__ unsigned xb_ld(unsigned* p)              { return __hip_atomic_load(p, __ATOMIC_RELAXED, __HIP_MEMORY_SCOPE_AGENT); }
; __device__ __forceinline__ unsigned xb_add(unsigned* p, unsigned v) { return __hip_atomic_fetch_add(p, v, __ATOMIC_RELAXED, __HIP_MEMORY_SCOPE_AGENT); }
; #define XB_SPIN(cond, bar) do { unsigned _sp = 0; while (cond) { __builtin_amdgcn_s_sleep(1); \
;     if ((++_sp & 255u) == 0u) { if (xb_ld(&(bar)[XB_TMO])) break; if (_sp > XB_SPIN_CAP) { atomicAdd(&(bar)[XB_TMO], 1u); break; } } } } while (0)
; __device__ __forceinline__ void xcd_barrier(const XcdBarrier& b) {
;     ...
;             const unsigned tg = og / nx;
;             if (og + 1u == (tg + 1u) * nx) xb_add(&bar[XB_TOPGEN], 1u);
;             else XB_SPIN(xb_ld(&bar[XB_TOPGEN]) == tg, bar);
;             __builtin_amdgcn_fence(__ATOMIC_ACQUIRE, "agent");
;             xb_add(&bar[XB_XGEN(b.x)], 1u);
;             asm volatile("s_waitcnt vmcnt(0)" ::: "memory");
;         } else {
;             XB_SPIN(xb_ld(&bar[XB_XGEN(b.x)]) == gen, bar);
;             __builtin_amdgcn_fence(__ATOMIC_ACQUIRE, "agent");
.LBB0_1467:
	s_and_b32 s5, s0, 0xff
	s_mov_b64 s[38:39], -1
	s_cmp_lg_u32 s5, 0
	s_mov_b64 s[42:43], -1
	s_nop 0
	s_cbranch_scc1 .LBB0_1470
	v_readlane_b32 s40, v251, 58
	v_readlane_b32 s41, v251, 59
	s_nop 4
	global_load_dword v0, v185, s[40:41] sc1
	s_waitcnt vmcnt(0)
	v_cmp_eq_u32_e32 vcc, 0, v0
	s_cbranch_vccnz .LBB0_1472
	s_mov_b64 s[42:43], 0
	s_mov_b64 s[40:41], -1
